# interleaved softmax streams: hazard s_nops that the partner stream's instruction already covers removed (selected P1/P2 and window tiles)
# baseline (speedup 1.0000x reference)
.Lsw_p1:
	v_lshl_add_u32 v114, s82, 2, v145
	ds_read2_b32 v[82:83], v114 offset0:127 offset1:128
	ds_read2_b32 v[84:85], v114 offset0:129 offset1:130
	ds_read2_b32 v[86:87], v114 offset0:143 offset1:144
	ds_read2_b32 v[88:89], v114 offset0:145 offset1:146
	s_waitcnt lgkmcnt(4)
	s_setprio 1
	v_mfma_f32_16x16x32_bf16 v[98:101], v[70:73], v[10:13], 0
	v_mfma_f32_16x16x32_bf16 v[102:105], v[74:77], v[10:13], 0
	v_mfma_f32_16x16x32_bf16 v[106:109], v[62:65], v[10:13], 0
	v_mfma_f32_16x16x32_bf16 v[110:113], v[54:57], v[10:13], 0
	ds_read2_b32 v[90:91], v114 offset0:159 offset1:160
	ds_read2_b32 v[92:93], v114 offset0:161 offset1:162
	ds_read2_b32 v[94:95], v114 offset0:175 offset1:176
	ds_read2_b32 v[96:97], v114 offset0:177 offset1:178
	v_mfma_f32_16x16x32_bf16 v[98:101], v[78:81], v[14:17], v[98:101]
	v_mfma_f32_16x16x32_bf16 v[102:105], v[66:69], v[14:17], v[102:105]
	v_mfma_f32_16x16x32_bf16 v[106:109], v[58:61], v[14:17], v[106:109]
	v_mfma_f32_16x16x32_bf16 v[110:113], v[50:53], v[14:17], v[110:113]
	v_mfma_f32_16x16x32_bf16 v[70:73], v[70:73], v[2:5], 0
	v_mfma_f32_16x16x32_bf16 v[74:77], v[74:77], v[2:5], 0
	v_mfma_f32_16x16x32_bf16 v[62:65], v[62:65], v[2:5], 0
	v_mfma_f32_16x16x32_bf16 v[54:57], v[54:57], v[2:5], 0
	v_mfma_f32_16x16x32_bf16 v[70:73], v[78:81], v[6:9], v[70:73]
	v_mfma_f32_16x16x32_bf16 v[74:77], v[66:69], v[6:9], v[74:77]
	v_mfma_f32_16x16x32_bf16 v[62:65], v[58:61], v[6:9], v[62:65]
	v_mfma_f32_16x16x32_bf16 v[54:57], v[50:53], v[6:9], v[54:57]
	s_setprio 0
	s_waitcnt lgkmcnt(0)
	ds_read2_b32 v[78:79], v114 offset0:111 offset1:112
	ds_read2_b32 v[80:81], v114 offset0:113 offset1:114
	ds_read2_b32 v[66:67], v114 offset0:127 offset1:128
	ds_read2_b32 v[68:69], v114 offset0:129 offset1:130
	ds_read2_b32 v[58:59], v114 offset0:143 offset1:144
	ds_read2_b32 v[60:61], v114 offset0:145 offset1:146
	ds_read2_b32 v[50:51], v114 offset0:159 offset1:160
	ds_read2_b32 v[52:53], v114 offset0:161 offset1:162
	v_pk_fma_f32 v[70:71], v[70:71], s[36:37], v[82:83] op_sel_hi:[1,0,1]
	v_pk_fma_f32 v[72:73], v[72:73], s[36:37], v[84:85] op_sel_hi:[1,0,1]
	v_pk_fma_f32 v[74:75], v[74:75], s[36:37], v[86:87] op_sel_hi:[1,0,1]
	v_pk_fma_f32 v[76:77], v[76:77], s[36:37], v[88:89] op_sel_hi:[1,0,1]
	v_pk_fma_f32 v[62:63], v[62:63], s[36:37], v[90:91] op_sel_hi:[1,0,1]
	v_pk_fma_f32 v[64:65], v[64:65], s[36:37], v[92:93] op_sel_hi:[1,0,1]
	v_pk_fma_f32 v[54:55], v[54:55], s[36:37], v[94:95] op_sel_hi:[1,0,1]
	v_pk_fma_f32 v[56:57], v[56:57], s[36:37], v[96:97] op_sel_hi:[1,0,1]
	s_waitcnt lgkmcnt(0)
	v_pk_fma_f32 v[98:99], v[98:99], s[36:37], v[78:79] op_sel_hi:[1,0,1]
	v_pk_fma_f32 v[100:101], v[100:101], s[36:37], v[80:81] op_sel_hi:[1,0,1]
	v_pk_fma_f32 v[102:103], v[102:103], s[36:37], v[66:67] op_sel_hi:[1,0,1]
	v_pk_fma_f32 v[104:105], v[104:105], s[36:37], v[68:69] op_sel_hi:[1,0,1]
	v_pk_fma_f32 v[106:107], v[106:107], s[36:37], v[58:59] op_sel_hi:[1,0,1]
	v_pk_fma_f32 v[108:109], v[108:109], s[36:37], v[60:61] op_sel_hi:[1,0,1]
	v_pk_fma_f32 v[110:111], v[110:111], s[36:37], v[50:51] op_sel_hi:[1,0,1]
	v_pk_fma_f32 v[112:113], v[112:113], s[36:37], v[52:53] op_sel_hi:[1,0,1]
	v_max3_f32 v116, v70, v71, v72
	v_max3_f32 v169, v98, v99, v100
	v_max3_f32 v116, v116, v73, v74
	v_max3_f32 v169, v169, v101, v102
	v_max3_f32 v116, v116, v75, v76
	v_max3_f32 v169, v169, v103, v104
	v_max3_f32 v116, v116, v77, v62
	v_max3_f32 v169, v169, v105, v106
	v_max3_f32 v116, v116, v63, v64
	v_max3_f32 v169, v169, v107, v108
	v_max3_f32 v116, v116, v65, v54
	v_max3_f32 v169, v169, v109, v110
	v_max3_f32 v116, v116, v55, v56
	v_max3_f32 v169, v169, v111, v112
	v_max3_f32 v116, v116, v57, s29
	v_max3_f32 v169, v169, v113, s29
	v_mov_b32_e32 v117, v116
	v_mov_b32_e32 v170, v169
	s_nop 0
	v_permlane16_swap_b32_e32 v116, v117
	v_permlane16_swap_b32_e32 v169, v170
	v_max_f32_e32 v116, v116, v117
	v_max_f32_e32 v169, v169, v170
	v_mov_b32_e32 v117, v116
	v_mov_b32_e32 v170, v169
	s_nop 0
	v_permlane32_swap_b32_e32 v116, v117
	v_permlane32_swap_b32_e32 v169, v170
	v_max_f32_e32 v116, v116, v117
	v_max_f32_e32 v169, v169, v170
	v_max_f32_e32 v121, v166, v116
	v_max_f32_e32 v175, v167, v169
	v_sub_f32_e32 v118, v166, v121
	v_sub_f32_e32 v172, v167, v175
	v_exp_f32_e32 v118, v118
	v_exp_f32_e32 v172, v172
	v_mov_b32_e32 v166, v121
	v_mov_b32_e32 v167, v175
	v_mov_b32_e32 v120, v121
	v_mov_b32_e32 v174, v175
	v_pk_mul_f32 v[46:47], v[46:47], v[118:119] op_sel_hi:[1,0]
	v_pk_mul_f32 v[30:31], v[30:31], v[172:173] op_sel_hi:[1,0]
	v_pk_mul_f32 v[48:49], v[48:49], v[118:119] op_sel_hi:[1,0]
	v_pk_mul_f32 v[32:33], v[32:33], v[172:173] op_sel_hi:[1,0]
	v_pk_mul_f32 v[42:43], v[42:43], v[118:119] op_sel_hi:[1,0]
	v_pk_mul_f32 v[26:27], v[26:27], v[172:173] op_sel_hi:[1,0]
	v_pk_mul_f32 v[44:45], v[44:45], v[118:119] op_sel_hi:[1,0]
	v_pk_mul_f32 v[28:29], v[28:29], v[172:173] op_sel_hi:[1,0]
	v_pk_mul_f32 v[38:39], v[38:39], v[118:119] op_sel_hi:[1,0]
	v_pk_mul_f32 v[22:23], v[22:23], v[172:173] op_sel_hi:[1,0]
	v_pk_mul_f32 v[40:41], v[40:41], v[118:119] op_sel_hi:[1,0]
	v_pk_mul_f32 v[24:25], v[24:25], v[172:173] op_sel_hi:[1,0]
	v_pk_mul_f32 v[34:35], v[34:35], v[118:119] op_sel_hi:[1,0]
	v_pk_mul_f32 v[18:19], v[18:19], v[172:173] op_sel_hi:[1,0]
	v_pk_mul_f32 v[36:37], v[36:37], v[118:119] op_sel_hi:[1,0]
	v_pk_mul_f32 v[20:21], v[20:21], v[172:173] op_sel_hi:[1,0]
	v_pk_add_f32 v[70:71], v[70:71], v[120:121] op_sel_hi:[1,0] neg_lo:[0,1] neg_hi:[0,1]
	v_pk_add_f32 v[98:99], v[98:99], v[174:175] op_sel_hi:[1,0] neg_lo:[0,1] neg_hi:[0,1]
	v_pk_add_f32 v[72:73], v[72:73], v[120:121] op_sel_hi:[1,0] neg_lo:[0,1] neg_hi:[0,1]
	v_pk_add_f32 v[100:101], v[100:101], v[174:175] op_sel_hi:[1,0] neg_lo:[0,1] neg_hi:[0,1]
	v_pk_add_f32 v[74:75], v[74:75], v[120:121] op_sel_hi:[1,0] neg_lo:[0,1] neg_hi:[0,1]
	v_pk_add_f32 v[102:103], v[102:103], v[174:175] op_sel_hi:[1,0] neg_lo:[0,1] neg_hi:[0,1]
	v_pk_add_f32 v[76:77], v[76:77], v[120:121] op_sel_hi:[1,0] neg_lo:[0,1] neg_hi:[0,1]
	v_pk_add_f32 v[104:105], v[104:105], v[174:175] op_sel_hi:[1,0] neg_lo:[0,1] neg_hi:[0,1]
	v_pk_add_f32 v[62:63], v[62:63], v[120:121] op_sel_hi:[1,0] neg_lo:[0,1] neg_hi:[0,1]
	v_pk_add_f32 v[106:107], v[106:107], v[174:175] op_sel_hi:[1,0] neg_lo:[0,1] neg_hi:[0,1]
	v_pk_add_f32 v[64:65], v[64:65], v[120:121] op_sel_hi:[1,0] neg_lo:[0,1] neg_hi:[0,1]
	v_pk_add_f32 v[108:109], v[108:109], v[174:175] op_sel_hi:[1,0] neg_lo:[0,1] neg_hi:[0,1]
	v_pk_add_f32 v[54:55], v[54:55], v[120:121] op_sel_hi:[1,0] neg_lo:[0,1] neg_hi:[0,1]
	v_pk_add_f32 v[110:111], v[110:111], v[174:175] op_sel_hi:[1,0] neg_lo:[0,1] neg_hi:[0,1]
	v_pk_add_f32 v[56:57], v[56:57], v[120:121] op_sel_hi:[1,0] neg_lo:[0,1] neg_hi:[0,1]
	v_pk_add_f32 v[112:113], v[112:113], v[174:175] op_sel_hi:[1,0] neg_lo:[0,1] neg_hi:[0,1]
	v_exp_f32_e32 v70, v70
	v_exp_f32_e32 v98, v98
	v_exp_f32_e32 v71, v71
	v_exp_f32_e32 v99, v99
	v_exp_f32_e32 v72, v72
	v_exp_f32_e32 v100, v100
	v_exp_f32_e32 v73, v73
	v_exp_f32_e32 v101, v101
	v_exp_f32_e32 v74, v74
	v_exp_f32_e32 v102, v102
	v_exp_f32_e32 v75, v75
	v_exp_f32_e32 v103, v103
	v_exp_f32_e32 v76, v76
	v_exp_f32_e32 v104, v104
	v_exp_f32_e32 v77, v77
	v_exp_f32_e32 v105, v105
	v_exp_f32_e32 v62, v62
	v_exp_f32_e32 v106, v106
	v_exp_f32_e32 v63, v63
	v_exp_f32_e32 v107, v107
	v_exp_f32_e32 v64, v64
	v_exp_f32_e32 v108, v108
	v_exp_f32_e32 v65, v65
	v_exp_f32_e32 v109, v109
	v_exp_f32_e32 v54, v54
	v_exp_f32_e32 v110, v110
	v_exp_f32_e32 v55, v55
	v_exp_f32_e32 v111, v111
	v_exp_f32_e32 v56, v56
	v_exp_f32_e32 v112, v112
	v_exp_f32_e32 v57, v57
	v_exp_f32_e32 v113, v113
	v_pk_add_f32 v[82:83], v[70:71], v[72:73]
	v_pk_add_f32 v[78:79], v[98:99], v[100:101]
	v_pk_add_f32 v[84:85], v[74:75], v[76:77]
	v_pk_add_f32 v[80:81], v[102:103], v[104:105]
	v_pk_add_f32 v[86:87], v[62:63], v[64:65]
	v_pk_add_f32 v[66:67], v[106:107], v[108:109]
	v_pk_add_f32 v[88:89], v[54:55], v[56:57]
	v_pk_add_f32 v[68:69], v[110:111], v[112:113]
	v_pk_add_f32 v[82:83], v[82:83], v[84:85]
	v_pk_add_f32 v[78:79], v[78:79], v[80:81]
	v_pk_add_f32 v[86:87], v[86:87], v[88:89]
	v_pk_add_f32 v[66:67], v[66:67], v[68:69]
	v_pk_add_f32 v[82:83], v[82:83], v[86:87]
	v_pk_add_f32 v[78:79], v[78:79], v[66:67]
	v_add_f32_e32 v82, v82, v83
	v_add_f32_e32 v78, v78, v79
	v_fma_f32 v158, v158, v118, v82
	v_fma_f32 v159, v159, v172, v78
	v_cvt_pk_bf16_f32 v77, v76, v77
	v_cvt_pk_bf16_f32 v105, v104, v105
	v_cvt_pk_bf16_f32 v76, v74, v75
	v_cvt_pk_bf16_f32 v104, v102, v103
	v_cvt_pk_bf16_f32 v75, v72, v73
	v_cvt_pk_bf16_f32 v103, v100, v101
	v_cvt_pk_bf16_f32 v74, v70, v71
	v_cvt_pk_bf16_f32 v102, v98, v99
	v_cvt_pk_bf16_f32 v62, v62, v63
	v_cvt_pk_bf16_f32 v106, v106, v107
	v_cvt_pk_bf16_f32 v63, v64, v65
	v_cvt_pk_bf16_f32 v107, v108, v109
	v_cvt_pk_bf16_f32 v64, v54, v55
	v_cvt_pk_bf16_f32 v108, v110, v111
	v_cvt_pk_bf16_f32 v65, v56, v57
	v_cvt_pk_bf16_f32 v109, v112, v113

.Lnw_p1:
	v_lshl_add_u32 v114, s25, 2, v145
	v_add_u32_e32 v115, 0xffc, v114
	v_add_u32_e32 v168, 0xfbc, v114
	ds_read2_b32 v[82:83], v115 offset1:1
	ds_read2_b32 v[84:85], v115 offset0:2 offset1:3
	ds_read2_b32 v[86:87], v115 offset0:16 offset1:17
	ds_read2_b32 v[88:89], v115 offset0:18 offset1:19
	s_waitcnt lgkmcnt(4)
	s_setprio 1
	v_mfma_f32_16x16x32_bf16 v[98:101], v[78:81], v[10:13], 0
	v_mfma_f32_16x16x32_bf16 v[102:105], v[70:73], v[10:13], 0
	v_mfma_f32_16x16x32_bf16 v[106:109], v[62:65], v[10:13], 0
	v_mfma_f32_16x16x32_bf16 v[110:113], v[54:57], v[10:13], 0
	ds_read2_b32 v[90:91], v115 offset0:32 offset1:33
	ds_read2_b32 v[92:93], v115 offset0:34 offset1:35
	ds_read2_b32 v[94:95], v115 offset0:48 offset1:49
	ds_read2_b32 v[96:97], v115 offset0:50 offset1:51
	v_mfma_f32_16x16x32_bf16 v[98:101], v[74:77], v[14:17], v[98:101]
	v_mfma_f32_16x16x32_bf16 v[102:105], v[66:69], v[14:17], v[102:105]
	v_mfma_f32_16x16x32_bf16 v[106:109], v[58:61], v[14:17], v[106:109]
	v_mfma_f32_16x16x32_bf16 v[110:113], v[50:53], v[14:17], v[110:113]
	v_mfma_f32_16x16x32_bf16 v[78:81], v[78:81], v[2:5], 0
	v_mfma_f32_16x16x32_bf16 v[70:73], v[70:73], v[2:5], 0
	v_mfma_f32_16x16x32_bf16 v[62:65], v[62:65], v[2:5], 0
	v_mfma_f32_16x16x32_bf16 v[54:57], v[54:57], v[2:5], 0
	v_mfma_f32_16x16x32_bf16 v[78:81], v[74:77], v[6:9], v[78:81]
	v_mfma_f32_16x16x32_bf16 v[70:73], v[66:69], v[6:9], v[70:73]
	v_mfma_f32_16x16x32_bf16 v[62:65], v[58:61], v[6:9], v[62:65]
	v_mfma_f32_16x16x32_bf16 v[54:57], v[50:53], v[6:9], v[54:57]
	s_setprio 0
	s_waitcnt lgkmcnt(0)
	ds_read2_b32 v[74:75], v168 offset1:1
	ds_read2_b32 v[76:77], v168 offset0:2 offset1:3
	ds_read2_b32 v[66:67], v168 offset0:16 offset1:17
	ds_read2_b32 v[68:69], v168 offset0:18 offset1:19
	ds_read2_b32 v[58:59], v168 offset0:32 offset1:33
	ds_read2_b32 v[60:61], v168 offset0:34 offset1:35
	ds_read2_b32 v[50:51], v168 offset0:48 offset1:49
	ds_read2_b32 v[52:53], v168 offset0:50 offset1:51
	v_pk_fma_f32 v[78:79], v[78:79], s[36:37], v[82:83] op_sel_hi:[1,0,1]
	v_pk_fma_f32 v[80:81], v[80:81], s[36:37], v[84:85] op_sel_hi:[1,0,1]
	v_pk_fma_f32 v[70:71], v[70:71], s[36:37], v[86:87] op_sel_hi:[1,0,1]
	v_pk_fma_f32 v[72:73], v[72:73], s[36:37], v[88:89] op_sel_hi:[1,0,1]
	v_pk_fma_f32 v[62:63], v[62:63], s[36:37], v[90:91] op_sel_hi:[1,0,1]
	v_pk_fma_f32 v[64:65], v[64:65], s[36:37], v[92:93] op_sel_hi:[1,0,1]
	v_pk_fma_f32 v[54:55], v[54:55], s[36:37], v[94:95] op_sel_hi:[1,0,1]
	v_pk_fma_f32 v[56:57], v[56:57], s[36:37], v[96:97] op_sel_hi:[1,0,1]
	s_waitcnt lgkmcnt(0)
	v_pk_fma_f32 v[98:99], v[98:99], s[36:37], v[74:75] op_sel_hi:[1,0,1]
	v_pk_fma_f32 v[100:101], v[100:101], s[36:37], v[76:77] op_sel_hi:[1,0,1]
	v_pk_fma_f32 v[102:103], v[102:103], s[36:37], v[66:67] op_sel_hi:[1,0,1]
	v_pk_fma_f32 v[104:105], v[104:105], s[36:37], v[68:69] op_sel_hi:[1,0,1]
	v_pk_fma_f32 v[106:107], v[106:107], s[36:37], v[58:59] op_sel_hi:[1,0,1]
	v_pk_fma_f32 v[108:109], v[108:109], s[36:37], v[60:61] op_sel_hi:[1,0,1]
	v_pk_fma_f32 v[110:111], v[110:111], s[36:37], v[50:51] op_sel_hi:[1,0,1]
	v_pk_fma_f32 v[112:113], v[112:113], s[36:37], v[52:53] op_sel_hi:[1,0,1]
	v_max3_f32 v116, v78, v79, v80
	v_max3_f32 v169, v98, v99, v100
	v_max3_f32 v116, v116, v81, v70
	v_max3_f32 v169, v169, v101, v102
	v_max3_f32 v116, v116, v71, v72
	v_max3_f32 v169, v169, v103, v104
	v_max3_f32 v116, v116, v73, v62
	v_max3_f32 v169, v169, v105, v106
	v_max3_f32 v116, v116, v63, v64
	v_max3_f32 v169, v169, v107, v108
	v_max3_f32 v116, v116, v65, v54
	v_max3_f32 v169, v169, v109, v110
	v_max3_f32 v116, v116, v55, v56
	v_max3_f32 v169, v169, v111, v112
	v_max3_f32 v116, v116, v57, s29
	v_max3_f32 v169, v169, v113, s29
	v_mov_b32_e32 v117, v116
	v_mov_b32_e32 v170, v169
	s_nop 0
	v_permlane16_swap_b32_e32 v116, v117
	v_permlane16_swap_b32_e32 v169, v170
	v_max_f32_e32 v116, v116, v117
	v_max_f32_e32 v169, v169, v170
	v_mov_b32_e32 v117, v116
	v_mov_b32_e32 v170, v169
	s_nop 0
	v_permlane32_swap_b32_e32 v116, v117
	v_permlane32_swap_b32_e32 v169, v170
	v_max_f32_e32 v116, v116, v117
	v_max_f32_e32 v169, v169, v170
	v_max_f32_e32 v121, v166, v116
	v_max_f32_e32 v175, v167, v169
	v_sub_f32_e32 v118, v166, v121
	v_sub_f32_e32 v172, v167, v175
	v_exp_f32_e32 v118, v118
	v_exp_f32_e32 v172, v172
	v_mov_b32_e32 v166, v121
	v_mov_b32_e32 v167, v175
	v_mov_b32_e32 v120, v121
	v_mov_b32_e32 v174, v175
	v_pk_mul_f32 v[46:47], v[46:47], v[118:119] op_sel_hi:[1,0]
	v_pk_mul_f32 v[30:31], v[30:31], v[172:173] op_sel_hi:[1,0]
	v_pk_mul_f32 v[48:49], v[48:49], v[118:119] op_sel_hi:[1,0]
	v_pk_mul_f32 v[32:33], v[32:33], v[172:173] op_sel_hi:[1,0]
	v_pk_mul_f32 v[42:43], v[42:43], v[118:119] op_sel_hi:[1,0]
	v_pk_mul_f32 v[26:27], v[26:27], v[172:173] op_sel_hi:[1,0]
	v_pk_mul_f32 v[44:45], v[44:45], v[118:119] op_sel_hi:[1,0]
	v_pk_mul_f32 v[28:29], v[28:29], v[172:173] op_sel_hi:[1,0]
	v_pk_mul_f32 v[38:39], v[38:39], v[118:119] op_sel_hi:[1,0]
	v_pk_mul_f32 v[22:23], v[22:23], v[172:173] op_sel_hi:[1,0]
	v_pk_mul_f32 v[40:41], v[40:41], v[118:119] op_sel_hi:[1,0]
	v_pk_mul_f32 v[24:25], v[24:25], v[172:173] op_sel_hi:[1,0]
	v_pk_mul_f32 v[34:35], v[34:35], v[118:119] op_sel_hi:[1,0]
	v_pk_mul_f32 v[18:19], v[18:19], v[172:173] op_sel_hi:[1,0]
	v_pk_mul_f32 v[36:37], v[36:37], v[118:119] op_sel_hi:[1,0]
	v_pk_mul_f32 v[20:21], v[20:21], v[172:173] op_sel_hi:[1,0]
	v_pk_add_f32 v[78:79], v[78:79], v[120:121] op_sel_hi:[1,0] neg_lo:[0,1] neg_hi:[0,1]
	v_pk_add_f32 v[98:99], v[98:99], v[174:175] op_sel_hi:[1,0] neg_lo:[0,1] neg_hi:[0,1]
	v_pk_add_f32 v[80:81], v[80:81], v[120:121] op_sel_hi:[1,0] neg_lo:[0,1] neg_hi:[0,1]
	v_pk_add_f32 v[100:101], v[100:101], v[174:175] op_sel_hi:[1,0] neg_lo:[0,1] neg_hi:[0,1]
	v_pk_add_f32 v[70:71], v[70:71], v[120:121] op_sel_hi:[1,0] neg_lo:[0,1] neg_hi:[0,1]
	v_pk_add_f32 v[102:103], v[102:103], v[174:175] op_sel_hi:[1,0] neg_lo:[0,1] neg_hi:[0,1]
	v_pk_add_f32 v[72:73], v[72:73], v[120:121] op_sel_hi:[1,0] neg_lo:[0,1] neg_hi:[0,1]
	v_pk_add_f32 v[104:105], v[104:105], v[174:175] op_sel_hi:[1,0] neg_lo:[0,1] neg_hi:[0,1]
	v_pk_add_f32 v[62:63], v[62:63], v[120:121] op_sel_hi:[1,0] neg_lo:[0,1] neg_hi:[0,1]
	v_pk_add_f32 v[106:107], v[106:107], v[174:175] op_sel_hi:[1,0] neg_lo:[0,1] neg_hi:[0,1]
	v_pk_add_f32 v[64:65], v[64:65], v[120:121] op_sel_hi:[1,0] neg_lo:[0,1] neg_hi:[0,1]
	v_pk_add_f32 v[108:109], v[108:109], v[174:175] op_sel_hi:[1,0] neg_lo:[0,1] neg_hi:[0,1]
	v_pk_add_f32 v[54:55], v[54:55], v[120:121] op_sel_hi:[1,0] neg_lo:[0,1] neg_hi:[0,1]
	v_pk_add_f32 v[110:111], v[110:111], v[174:175] op_sel_hi:[1,0] neg_lo:[0,1] neg_hi:[0,1]
	v_pk_add_f32 v[56:57], v[56:57], v[120:121] op_sel_hi:[1,0] neg_lo:[0,1] neg_hi:[0,1]
	v_pk_add_f32 v[112:113], v[112:113], v[174:175] op_sel_hi:[1,0] neg_lo:[0,1] neg_hi:[0,1]
	v_exp_f32_e32 v78, v78
	v_exp_f32_e32 v98, v98
	v_exp_f32_e32 v79, v79
	v_exp_f32_e32 v99, v99
	v_exp_f32_e32 v80, v80
	v_exp_f32_e32 v100, v100
	v_exp_f32_e32 v81, v81
	v_exp_f32_e32 v101, v101
	v_exp_f32_e32 v70, v70
	v_exp_f32_e32 v102, v102
	v_exp_f32_e32 v71, v71
	v_exp_f32_e32 v103, v103
	v_exp_f32_e32 v72, v72
	v_exp_f32_e32 v104, v104
	v_exp_f32_e32 v73, v73
	v_exp_f32_e32 v105, v105
	v_exp_f32_e32 v62, v62
	v_exp_f32_e32 v106, v106
	v_exp_f32_e32 v63, v63
	v_exp_f32_e32 v107, v107
	v_exp_f32_e32 v64, v64
	v_exp_f32_e32 v108, v108
	v_exp_f32_e32 v65, v65
	v_exp_f32_e32 v109, v109
	v_exp_f32_e32 v54, v54
	v_exp_f32_e32 v110, v110
	v_exp_f32_e32 v55, v55
	v_exp_f32_e32 v111, v111
	v_exp_f32_e32 v56, v56
	v_exp_f32_e32 v112, v112
	v_exp_f32_e32 v57, v57
	v_exp_f32_e32 v113, v113
	v_pk_add_f32 v[82:83], v[78:79], v[80:81]
	v_pk_add_f32 v[74:75], v[98:99], v[100:101]
	v_pk_add_f32 v[84:85], v[70:71], v[72:73]
	v_pk_add_f32 v[76:77], v[102:103], v[104:105]
	v_pk_add_f32 v[86:87], v[62:63], v[64:65]
	v_pk_add_f32 v[66:67], v[106:107], v[108:109]
	v_pk_add_f32 v[88:89], v[54:55], v[56:57]
	v_pk_add_f32 v[68:69], v[110:111], v[112:113]
	v_pk_add_f32 v[82:83], v[82:83], v[84:85]
	v_pk_add_f32 v[74:75], v[74:75], v[76:77]
	v_pk_add_f32 v[86:87], v[86:87], v[88:89]
	v_pk_add_f32 v[66:67], v[66:67], v[68:69]
	v_pk_add_f32 v[82:83], v[82:83], v[86:87]
	v_pk_add_f32 v[74:75], v[74:75], v[66:67]
	v_add_f32_e32 v82, v82, v83
	v_add_f32_e32 v74, v74, v75
	v_fma_f32 v160, v160, v118, v82
	v_fma_f32 v161, v161, v172, v74
	v_cvt_pk_bf16_f32 v73, v72, v73
	v_cvt_pk_bf16_f32 v105, v104, v105
	v_cvt_pk_bf16_f32 v72, v70, v71
	v_cvt_pk_bf16_f32 v104, v102, v103
	v_cvt_pk_bf16_f32 v71, v80, v81
	v_cvt_pk_bf16_f32 v103, v100, v101
	v_cvt_pk_bf16_f32 v70, v78, v79
	v_cvt_pk_bf16_f32 v102, v98, v99
	v_cvt_pk_bf16_f32 v62, v62, v63
	v_cvt_pk_bf16_f32 v106, v106, v107
	v_cvt_pk_bf16_f32 v63, v64, v65
	v_cvt_pk_bf16_f32 v107, v108, v109
	v_cvt_pk_bf16_f32 v64, v54, v55
	v_cvt_pk_bf16_f32 v108, v110, v111
	v_cvt_pk_bf16_f32 v65, v56, v57
	v_cvt_pk_bf16_f32 v109, v112, v113

.LBB0_430:
	s_andn2_b64 vcc, exec, s[6:7]
	s_cbranch_vccnz .LBB0_438
	v_cmp_ne_u32_e32 vcc, 0, v139
	s_cbranch_vccz .Lsel_fast
	v_add_u32_e32 v54, s13, v196
	v_sub_u32_e32 v0, s14, v140
	v_add_u32_e32 v62, v54, v194
	v_add_u32_e32 v89, v54, v195
	v_lshl_add_u32 v0, v0, 2, v216
	s_cmp_lg_u64 s[44:45], 0
	s_movk_i32 s98, 0xfec
	s_cselect_b32 s98, 0xffc, s98
	v_add_u32_e32 v230, s98, v0
	v_add_u32_e32 v231, 0xfec, v0
	ds_read_b128 v[64:67], v62 offset:16384
	ds_read_b128 v[54:57], v89 offset:16384
	ds_read_b128 v[68:71], v62 offset:18432
	ds_read_b128 v[58:61], v89 offset:18432
	ds_read_b128 v[72:75], v62 offset:20480
	ds_read_b128 v[76:79], v89 offset:20480
	ds_read_b128 v[80:83], v62 offset:22528
	ds_read_b128 v[84:87], v89 offset:22528
	ds_read2_b32 v[90:91], v230 offset1:1
	ds_read2_b32 v[92:93], v230 offset0:2 offset1:3
	ds_read2_b32 v[94:95], v230 offset0:16 offset1:17
	ds_read2_b32 v[96:97], v230 offset0:18 offset1:19
	s_waitcnt lgkmcnt(4)
	ds_read2_b32 v[98:99], v230 offset0:32 offset1:33
	ds_read2_b32 v[100:101], v230 offset0:34 offset1:35
	ds_read2_b32 v[154:155], v230 offset0:48 offset1:49
	ds_read2_b32 v[156:157], v230 offset0:50 offset1:51
	s_cbranch_scc0 .Lp1v_m1
	s_cmp_lg_u64 s[42:43], 0
	s_cbranch_scc0 .Lp1v_only0
	s_setprio 1
	v_mfma_f32_16x16x32_bf16 v[170:173], v[64:67], v[2:5], 0
	v_mfma_f32_16x16x32_bf16 v[174:177], v[68:71], v[2:5], 0
	v_mfma_f32_16x16x32_bf16 v[170:173], v[54:57], v[6:9], v[170:173]
	v_mfma_f32_16x16x32_bf16 v[178:181], v[72:75], v[2:5], 0
	v_mfma_f32_16x16x32_bf16 v[174:177], v[58:61], v[6:9], v[174:177]
	v_mfma_f32_16x16x32_bf16 v[182:185], v[80:83], v[2:5], 0
	v_mfma_f32_16x16x32_bf16 v[178:181], v[76:79], v[6:9], v[178:181]
	v_mfma_f32_16x16x32_bf16 v[182:185], v[84:87], v[6:9], v[182:185]
	v_mfma_f32_16x16x32_bf16 v[64:67], v[64:67], v[10:13], 0
	v_mfma_f32_16x16x32_bf16 v[68:71], v[68:71], v[10:13], 0
	v_mfma_f32_16x16x32_bf16 v[64:67], v[54:57], v[14:17], v[64:67]
	v_mfma_f32_16x16x32_bf16 v[72:75], v[72:75], v[10:13], 0
	v_mfma_f32_16x16x32_bf16 v[68:71], v[58:61], v[14:17], v[68:71]
	v_mfma_f32_16x16x32_bf16 v[80:83], v[80:83], v[10:13], 0
	v_mfma_f32_16x16x32_bf16 v[72:75], v[76:79], v[14:17], v[72:75]
	v_mfma_f32_16x16x32_bf16 v[80:83], v[84:87], v[14:17], v[80:83]
	s_setprio 0
	s_waitcnt lgkmcnt(0)
	v_pk_fma_f32 v[170:171], v[170:171], s[36:37], v[90:91] op_sel_hi:[1,0,1]
	v_pk_fma_f32 v[172:173], v[172:173], s[36:37], v[92:93] op_sel_hi:[1,0,1]
	v_pk_fma_f32 v[174:175], v[174:175], s[36:37], v[94:95] op_sel_hi:[1,0,1]
	v_pk_fma_f32 v[176:177], v[176:177], s[36:37], v[96:97] op_sel_hi:[1,0,1]
	v_pk_fma_f32 v[178:179], v[178:179], s[36:37], v[98:99] op_sel_hi:[1,0,1]
	v_pk_fma_f32 v[180:181], v[180:181], s[36:37], v[100:101] op_sel_hi:[1,0,1]
	v_pk_fma_f32 v[182:183], v[182:183], s[36:37], v[154:155] op_sel_hi:[1,0,1]
	v_pk_fma_f32 v[184:185], v[184:185], s[36:37], v[156:157] op_sel_hi:[1,0,1]
	ds_read2_b32 v[90:91], v231 offset1:1
	ds_read2_b32 v[92:93], v231 offset0:2 offset1:3
	ds_read2_b32 v[94:95], v231 offset0:16 offset1:17
	ds_read2_b32 v[96:97], v231 offset0:18 offset1:19
	ds_read2_b32 v[98:99], v231 offset0:32 offset1:33
	ds_read2_b32 v[100:101], v231 offset0:34 offset1:35
	ds_read2_b32 v[154:155], v231 offset0:48 offset1:49
	ds_read2_b32 v[156:157], v231 offset0:50 offset1:51
	v_max3_f32 v186, v170, v171, v172
	v_max3_f32 v186, v186, v173, v174
	v_max3_f32 v186, v186, v175, v176
	v_max3_f32 v186, v186, v177, v178
	v_max3_f32 v186, v186, v179, v180
	v_max3_f32 v186, v186, v181, v182
	v_max3_f32 v186, v186, v183, v184
	v_max3_f32 v186, v186, v185, s29
	v_mov_b32_e32 v187, v186
	s_nop 1
	v_permlane16_swap_b32_e32 v186, v187
	v_max_f32_e32 v186, v186, v187
	v_mov_b32_e32 v187, v186
	s_nop 1
	v_permlane32_swap_b32_e32 v186, v187
	v_max_f32_e32 v186, v186, v187
	v_cndmask_b32_e64 v186, v148, v186, s[44:45]
	v_max_f32_e32 v187, v160, v186
	s_waitcnt lgkmcnt(0)
	v_pk_fma_f32 v[64:65], v[64:65], s[36:37], v[90:91] op_sel_hi:[1,0,1]
	v_pk_fma_f32 v[66:67], v[66:67], s[36:37], v[92:93] op_sel_hi:[1,0,1]
	v_pk_fma_f32 v[68:69], v[68:69], s[36:37], v[94:95] op_sel_hi:[1,0,1]
	v_pk_fma_f32 v[70:71], v[70:71], s[36:37], v[96:97] op_sel_hi:[1,0,1]
	v_pk_fma_f32 v[72:73], v[72:73], s[36:37], v[98:99] op_sel_hi:[1,0,1]
	v_pk_fma_f32 v[74:75], v[74:75], s[36:37], v[100:101] op_sel_hi:[1,0,1]
	v_pk_fma_f32 v[80:81], v[80:81], s[36:37], v[154:155] op_sel_hi:[1,0,1]
	v_pk_fma_f32 v[82:83], v[82:83], s[36:37], v[156:157] op_sel_hi:[1,0,1]
	v_max3_f32 v76, v64, v65, v66
	v_max3_f32 v76, v76, v67, v68
	v_max3_f32 v76, v76, v69, v70
	v_max3_f32 v76, v76, v71, v72
	v_max3_f32 v76, v76, v73, v74
	v_max3_f32 v76, v76, v75, v80
	v_max3_f32 v76, v76, v81, v82
	v_max3_f32 v76, v76, v83, s29
	v_mov_b32_e32 v77, v76
	s_nop 1
	v_permlane16_swap_b32_e32 v76, v77
	v_max_f32_e32 v76, v76, v77
	v_mov_b32_e32 v77, v76
	s_nop 1
	v_permlane32_swap_b32_e32 v76, v77
	v_max_f32_e32 v76, v76, v77
	v_cndmask_b32_e64 v76, v148, v76, s[42:43]
	v_max_f32_e32 v77, v161, v76
	v_sub_f32_e32 v248, v160, v187
	v_sub_f32_e32 v0, v161, v77
	v_exp_f32_e32 v236, v248
	v_exp_f32_e32 v0, v0
	v_cndmask_b32_e64 v246, v209, v187, s[44:45]
	v_cndmask_b32_e64 v78, v209, v77, s[42:43]
	v_mov_b32_e32 v160, v187
	v_mov_b32_e32 v161, v77
	v_pk_mul_f32 v[36:37], v[36:37], v[236:237] op_sel_hi:[1,0]
	v_pk_mul_f32 v[32:33], v[32:33], v[0:1] op_sel_hi:[1,0]
	v_pk_mul_f32 v[34:35], v[34:35], v[236:237] op_sel_hi:[1,0]
	v_pk_mul_f32 v[30:31], v[30:31], v[0:1] op_sel_hi:[1,0]
	v_pk_mul_f32 v[48:49], v[48:49], v[236:237] op_sel_hi:[1,0]
	v_pk_mul_f32 v[28:29], v[28:29], v[0:1] op_sel_hi:[1,0]
	v_pk_mul_f32 v[46:47], v[46:47], v[236:237] op_sel_hi:[1,0]
	v_pk_mul_f32 v[26:27], v[26:27], v[0:1] op_sel_hi:[1,0]
	v_pk_mul_f32 v[44:45], v[44:45], v[236:237] op_sel_hi:[1,0]
	v_pk_mul_f32 v[24:25], v[24:25], v[0:1] op_sel_hi:[1,0]
	v_pk_mul_f32 v[42:43], v[42:43], v[236:237] op_sel_hi:[1,0]
	v_pk_mul_f32 v[22:23], v[22:23], v[0:1] op_sel_hi:[1,0]
	v_pk_mul_f32 v[52:53], v[52:53], v[236:237] op_sel_hi:[1,0]
	v_pk_mul_f32 v[20:21], v[20:21], v[0:1] op_sel_hi:[1,0]
	v_pk_mul_f32 v[50:51], v[50:51], v[236:237] op_sel_hi:[1,0]
	v_pk_mul_f32 v[18:19], v[18:19], v[0:1] op_sel_hi:[1,0]
	v_pk_add_f32 v[170:171], v[170:171], v[246:247] op_sel_hi:[1,0] neg_lo:[0,1] neg_hi:[0,1]
	v_pk_add_f32 v[64:65], v[64:65], v[78:79] op_sel_hi:[1,0] neg_lo:[0,1] neg_hi:[0,1]
	v_pk_add_f32 v[172:173], v[172:173], v[246:247] op_sel_hi:[1,0] neg_lo:[0,1] neg_hi:[0,1]
	v_pk_add_f32 v[66:67], v[66:67], v[78:79] op_sel_hi:[1,0] neg_lo:[0,1] neg_hi:[0,1]
	v_pk_add_f32 v[174:175], v[174:175], v[246:247] op_sel_hi:[1,0] neg_lo:[0,1] neg_hi:[0,1]
	v_pk_add_f32 v[68:69], v[68:69], v[78:79] op_sel_hi:[1,0] neg_lo:[0,1] neg_hi:[0,1]
	v_pk_add_f32 v[176:177], v[176:177], v[246:247] op_sel_hi:[1,0] neg_lo:[0,1] neg_hi:[0,1]
	v_pk_add_f32 v[70:71], v[70:71], v[78:79] op_sel_hi:[1,0] neg_lo:[0,1] neg_hi:[0,1]
	v_pk_add_f32 v[178:179], v[178:179], v[246:247] op_sel_hi:[1,0] neg_lo:[0,1] neg_hi:[0,1]
	v_pk_add_f32 v[72:73], v[72:73], v[78:79] op_sel_hi:[1,0] neg_lo:[0,1] neg_hi:[0,1]
	v_pk_add_f32 v[180:181], v[180:181], v[246:247] op_sel_hi:[1,0] neg_lo:[0,1] neg_hi:[0,1]
	v_pk_add_f32 v[74:75], v[74:75], v[78:79] op_sel_hi:[1,0] neg_lo:[0,1] neg_hi:[0,1]
	v_pk_add_f32 v[182:183], v[182:183], v[246:247] op_sel_hi:[1,0] neg_lo:[0,1] neg_hi:[0,1]
	v_pk_add_f32 v[80:81], v[80:81], v[78:79] op_sel_hi:[1,0] neg_lo:[0,1] neg_hi:[0,1]
	v_pk_add_f32 v[184:185], v[184:185], v[246:247] op_sel_hi:[1,0] neg_lo:[0,1] neg_hi:[0,1]
	v_pk_add_f32 v[82:83], v[82:83], v[78:79] op_sel_hi:[1,0] neg_lo:[0,1] neg_hi:[0,1]
	v_exp_f32_e32 v170, v170
	v_exp_f32_e32 v64, v64
	v_exp_f32_e32 v171, v171
	v_exp_f32_e32 v65, v65
	v_exp_f32_e32 v172, v172
	v_exp_f32_e32 v66, v66
	v_exp_f32_e32 v173, v173
	v_exp_f32_e32 v67, v67
	v_exp_f32_e32 v174, v174
	v_exp_f32_e32 v68, v68
	v_exp_f32_e32 v175, v175
	v_exp_f32_e32 v69, v69
	v_exp_f32_e32 v176, v176
	v_exp_f32_e32 v70, v70
	v_exp_f32_e32 v177, v177
	v_exp_f32_e32 v71, v71
	v_exp_f32_e32 v178, v178
	v_exp_f32_e32 v72, v72
	v_exp_f32_e32 v179, v179
	v_exp_f32_e32 v73, v73
	v_exp_f32_e32 v180, v180
	v_exp_f32_e32 v74, v74
	v_exp_f32_e32 v181, v181
	v_exp_f32_e32 v75, v75
	v_exp_f32_e32 v182, v182
	v_exp_f32_e32 v80, v80
	v_exp_f32_e32 v183, v183
	v_exp_f32_e32 v81, v81
	v_exp_f32_e32 v184, v184
	v_exp_f32_e32 v82, v82
	v_exp_f32_e32 v185, v185
	v_exp_f32_e32 v83, v83
	v_pk_add_f32 v[238:239], v[170:171], v[172:173]
	v_pk_add_f32 v[84:85], v[64:65], v[66:67]
	v_pk_add_f32 v[240:241], v[174:175], v[176:177]
	v_pk_add_f32 v[86:87], v[68:69], v[70:71]
	v_pk_add_f32 v[242:243], v[178:179], v[180:181]
	v_pk_add_f32 v[76:77], v[72:73], v[74:75]
	v_pk_add_f32 v[244:245], v[182:183], v[184:185]
	v_pk_add_f32 v[78:79], v[80:81], v[82:83]
	v_pk_add_f32 v[238:239], v[238:239], v[240:241]
	v_pk_add_f32 v[84:85], v[84:85], v[86:87]
	v_pk_add_f32 v[242:243], v[242:243], v[244:245]
	v_pk_add_f32 v[76:77], v[76:77], v[78:79]
	v_pk_add_f32 v[238:239], v[238:239], v[242:243]
	v_pk_add_f32 v[84:85], v[84:85], v[76:77]
	v_add_f32_e32 v238, v238, v239
	v_add_f32_e32 v84, v84, v85
	v_fma_f32 v144, v144, v236, v238
	v_fma_f32 v145, v145, v0, v84
	v_cvt_pk_bf16_f32 v58, v170, v171
	v_cvt_pk_bf16_f32 v67, v66, v67
	v_cvt_pk_bf16_f32 v59, v172, v173
	v_cvt_pk_bf16_f32 v66, v64, v65
	v_cvt_pk_bf16_f32 v60, v174, v175
	v_cvt_pk_bf16_f32 v68, v68, v69
	v_cvt_pk_bf16_f32 v61, v176, v177
	v_cvt_pk_bf16_f32 v69, v70, v71
	v_cvt_pk_bf16_f32 v54, v178, v179
	v_cvt_pk_bf16_f32 v62, v72, v73
	v_cvt_pk_bf16_f32 v55, v180, v181
	v_cvt_pk_bf16_f32 v63, v74, v75
	v_cvt_pk_bf16_f32 v56, v182, v183
	v_cvt_pk_bf16_f32 v64, v80, v81
	v_cvt_pk_bf16_f32 v57, v184, v185
	v_cvt_pk_bf16_f32 v65, v82, v83
	s_branch .LBB0_446

.LBB0_439:
	s_andn2_b64 vcc, exec, s[6:7]
	s_cbranch_vccnz .LBB0_448
	v_and_b32_e32 v0, 1, v164
	v_cmp_eq_u32_e64 s[42:43], 1, v0
	v_and_b32_e32 v0, 1, v162
	v_cmp_eq_u32_e64 s[44:45], 1, v0
	s_or_b64 s[6:7], s[44:45], s[42:43]
	v_cndmask_b32_e64 v54, 0, 1, s[6:7]
	v_cmp_ne_u32_e32 vcc, 0, v54
	s_cbranch_vccz .Lsel_fast
	v_add_u32_e32 v54, s13, v196
	v_add_u32_e32 v62, v54, v194
	v_add_u32_e32 v0, v54, v195
	s_cmp_lg_u64 s[44:45], 0
	ds_read_b128 v[64:67], v62 offset:16384
	ds_read_b128 v[54:57], v0 offset:16384
	ds_read_b128 v[68:71], v62 offset:18432
	ds_read_b128 v[58:61], v0 offset:18432
	ds_read_b128 v[72:75], v62 offset:20480
	ds_read_b128 v[76:79], v0 offset:20480
	ds_read_b128 v[80:83], v62 offset:22528
	ds_read_b128 v[84:87], v0 offset:22528
	ds_read_b32 v188, v193
	s_waitcnt lgkmcnt(0)
	s_cbranch_scc0 .Lp2v_m1
	s_cmp_lg_u64 s[42:43], 0
	s_cbranch_scc0 .Lp2v_only0
	s_setprio 1
	v_mfma_f32_16x16x32_bf16 v[170:173], v[64:67], v[2:5], 0
	v_mfma_f32_16x16x32_bf16 v[174:177], v[68:71], v[2:5], 0
	v_mfma_f32_16x16x32_bf16 v[170:173], v[54:57], v[6:9], v[170:173]
	v_mfma_f32_16x16x32_bf16 v[178:181], v[72:75], v[2:5], 0
	v_mfma_f32_16x16x32_bf16 v[174:177], v[58:61], v[6:9], v[174:177]
	v_mfma_f32_16x16x32_bf16 v[182:185], v[80:83], v[2:5], 0
	v_mfma_f32_16x16x32_bf16 v[178:181], v[76:79], v[6:9], v[178:181]
	v_mfma_f32_16x16x32_bf16 v[182:185], v[84:87], v[6:9], v[182:185]
	v_mfma_f32_16x16x32_bf16 v[64:67], v[64:67], v[10:13], 0
	v_mfma_f32_16x16x32_bf16 v[68:71], v[68:71], v[10:13], 0
	v_mfma_f32_16x16x32_bf16 v[64:67], v[54:57], v[14:17], v[64:67]
	v_mfma_f32_16x16x32_bf16 v[72:75], v[72:75], v[10:13], 0
	v_mfma_f32_16x16x32_bf16 v[68:71], v[58:61], v[14:17], v[68:71]
	v_mfma_f32_16x16x32_bf16 v[80:83], v[80:83], v[10:13], 0
	v_mfma_f32_16x16x32_bf16 v[72:75], v[76:79], v[14:17], v[72:75]
	v_mfma_f32_16x16x32_bf16 v[80:83], v[84:87], v[14:17], v[80:83]
	s_setprio 0
	s_nop 7
	v_max3_f32 v186, v170, v171, v172
	v_max3_f32 v76, v64, v65, v66
	v_max3_f32 v186, v186, v173, v174
	v_max3_f32 v76, v76, v67, v68
	v_max3_f32 v186, v186, v175, v176
	v_max3_f32 v76, v76, v69, v70
	v_max3_f32 v186, v186, v177, v178
	v_max3_f32 v76, v76, v71, v72
	v_max3_f32 v186, v186, v179, v180
	v_max3_f32 v76, v76, v73, v74
	v_max3_f32 v186, v186, v181, v182
	v_max3_f32 v76, v76, v75, v80
	v_max3_f32 v186, v186, v183, v184
	v_max3_f32 v76, v76, v81, v82
	v_max_f32_e32 v186, v186, v185
	v_max_f32_e32 v76, v76, v83
	v_mov_b32_e32 v187, v186
	v_mov_b32_e32 v77, v76
	s_nop 0
	v_permlane16_swap_b32_e32 v186, v187
	v_permlane16_swap_b32_e32 v76, v77
	v_max_f32_e32 v186, v186, v187
	v_max_f32_e32 v76, v76, v77
	v_mov_b32_e32 v187, v186
	v_mov_b32_e32 v77, v76
	s_nop 0
	v_permlane32_swap_b32_e32 v186, v187
	v_permlane32_swap_b32_e32 v76, v77
	v_max_f32_e32 v186, v186, v187
	v_max_f32_e32 v76, v76, v77
	v_fma_f32 v186, v186, s36, v188
	v_fma_f32 v76, v76, s36, v188
	v_max_f32_e32 v186, s29, v186
	v_max_f32_e32 v76, s29, v76
	v_cndmask_b32_e64 v186, v148, v186, s[44:45]
	v_cndmask_b32_e64 v76, v148, v76, s[42:43]
	v_max_f32_e32 v187, v160, v186
	v_max_f32_e32 v77, v161, v76
	v_sub_f32_e32 v248, v160, v187
	v_sub_f32_e32 v0, v161, v77
	v_exp_f32_e32 v236, v248
	v_exp_f32_e32 v0, v0
	v_cndmask_b32_e64 v186, v209, v187, s[44:45]
	v_cndmask_b32_e64 v76, v209, v77, s[42:43]
	v_mov_b32_e32 v160, v187
	v_mov_b32_e32 v161, v77
	v_sub_f32_e32 v246, v188, v186
	v_sub_f32_e32 v78, v188, v76
	v_pk_mul_f32 v[36:37], v[36:37], v[236:237] op_sel_hi:[1,0]
	v_pk_mul_f32 v[32:33], v[32:33], v[0:1] op_sel_hi:[1,0]
	v_pk_mul_f32 v[34:35], v[34:35], v[236:237] op_sel_hi:[1,0]
	v_pk_mul_f32 v[30:31], v[30:31], v[0:1] op_sel_hi:[1,0]
	v_pk_mul_f32 v[48:49], v[48:49], v[236:237] op_sel_hi:[1,0]
	v_pk_mul_f32 v[28:29], v[28:29], v[0:1] op_sel_hi:[1,0]
	v_pk_mul_f32 v[46:47], v[46:47], v[236:237] op_sel_hi:[1,0]
	v_pk_mul_f32 v[26:27], v[26:27], v[0:1] op_sel_hi:[1,0]
	v_pk_mul_f32 v[44:45], v[44:45], v[236:237] op_sel_hi:[1,0]
	v_pk_mul_f32 v[24:25], v[24:25], v[0:1] op_sel_hi:[1,0]
	v_pk_mul_f32 v[42:43], v[42:43], v[236:237] op_sel_hi:[1,0]
	v_pk_mul_f32 v[22:23], v[22:23], v[0:1] op_sel_hi:[1,0]
	v_pk_mul_f32 v[52:53], v[52:53], v[236:237] op_sel_hi:[1,0]
	v_pk_mul_f32 v[20:21], v[20:21], v[0:1] op_sel_hi:[1,0]
	v_pk_mul_f32 v[50:51], v[50:51], v[236:237] op_sel_hi:[1,0]
	v_pk_mul_f32 v[18:19], v[18:19], v[0:1] op_sel_hi:[1,0]
	v_pk_fma_f32 v[170:171], v[170:171], s[36:37], v[246:247] op_sel_hi:[1,0,0]
	v_pk_fma_f32 v[64:65], v[64:65], s[36:37], v[78:79] op_sel_hi:[1,0,0]
	v_pk_fma_f32 v[172:173], v[172:173], s[36:37], v[246:247] op_sel_hi:[1,0,0]
	v_pk_fma_f32 v[66:67], v[66:67], s[36:37], v[78:79] op_sel_hi:[1,0,0]
	v_pk_fma_f32 v[174:175], v[174:175], s[36:37], v[246:247] op_sel_hi:[1,0,0]
	v_pk_fma_f32 v[68:69], v[68:69], s[36:37], v[78:79] op_sel_hi:[1,0,0]
	v_pk_fma_f32 v[176:177], v[176:177], s[36:37], v[246:247] op_sel_hi:[1,0,0]
	v_pk_fma_f32 v[70:71], v[70:71], s[36:37], v[78:79] op_sel_hi:[1,0,0]
	v_pk_fma_f32 v[178:179], v[178:179], s[36:37], v[246:247] op_sel_hi:[1,0,0]
	v_pk_fma_f32 v[72:73], v[72:73], s[36:37], v[78:79] op_sel_hi:[1,0,0]
	v_pk_fma_f32 v[180:181], v[180:181], s[36:37], v[246:247] op_sel_hi:[1,0,0]
	v_pk_fma_f32 v[74:75], v[74:75], s[36:37], v[78:79] op_sel_hi:[1,0,0]
	v_pk_fma_f32 v[182:183], v[182:183], s[36:37], v[246:247] op_sel_hi:[1,0,0]
	v_pk_fma_f32 v[80:81], v[80:81], s[36:37], v[78:79] op_sel_hi:[1,0,0]
	v_pk_fma_f32 v[184:185], v[184:185], s[36:37], v[246:247] op_sel_hi:[1,0,0]
	v_pk_fma_f32 v[82:83], v[82:83], s[36:37], v[78:79] op_sel_hi:[1,0,0]
	v_exp_f32_e32 v170, v170
	v_exp_f32_e32 v64, v64
	v_exp_f32_e32 v171, v171
	v_exp_f32_e32 v65, v65
	v_exp_f32_e32 v172, v172
	v_exp_f32_e32 v66, v66
	v_exp_f32_e32 v173, v173
	v_exp_f32_e32 v67, v67
	v_exp_f32_e32 v174, v174
	v_exp_f32_e32 v68, v68
	v_exp_f32_e32 v175, v175
	v_exp_f32_e32 v69, v69
	v_exp_f32_e32 v176, v176
	v_exp_f32_e32 v70, v70
	v_exp_f32_e32 v177, v177
	v_exp_f32_e32 v71, v71
	v_exp_f32_e32 v178, v178
	v_exp_f32_e32 v72, v72
	v_exp_f32_e32 v179, v179
	v_exp_f32_e32 v73, v73
	v_exp_f32_e32 v180, v180
	v_exp_f32_e32 v74, v74
	v_exp_f32_e32 v181, v181
	v_exp_f32_e32 v75, v75
	v_exp_f32_e32 v182, v182
	v_exp_f32_e32 v80, v80
	v_exp_f32_e32 v183, v183
	v_exp_f32_e32 v81, v81
	v_exp_f32_e32 v184, v184
	v_exp_f32_e32 v82, v82
	v_exp_f32_e32 v185, v185
	v_exp_f32_e32 v83, v83
	v_pk_add_f32 v[238:239], v[170:171], v[172:173]
	v_pk_add_f32 v[84:85], v[64:65], v[66:67]
	v_pk_add_f32 v[240:241], v[174:175], v[176:177]
	v_pk_add_f32 v[86:87], v[68:69], v[70:71]
	v_pk_add_f32 v[242:243], v[178:179], v[180:181]
	v_pk_add_f32 v[76:77], v[72:73], v[74:75]
	v_pk_add_f32 v[244:245], v[182:183], v[184:185]
	v_pk_add_f32 v[78:79], v[80:81], v[82:83]
	v_pk_add_f32 v[238:239], v[238:239], v[240:241]
	v_pk_add_f32 v[84:85], v[84:85], v[86:87]
	v_pk_add_f32 v[242:243], v[242:243], v[244:245]
	v_pk_add_f32 v[76:77], v[76:77], v[78:79]
	v_pk_add_f32 v[238:239], v[238:239], v[242:243]
	v_pk_add_f32 v[84:85], v[84:85], v[76:77]
	v_add_f32_e32 v238, v238, v239
	v_add_f32_e32 v84, v84, v85
	v_fma_f32 v144, v144, v236, v238
	v_fma_f32 v145, v145, v0, v84
	v_cvt_pk_bf16_f32 v58, v170, v171
	v_cvt_pk_bf16_f32 v67, v66, v67
	v_cvt_pk_bf16_f32 v59, v172, v173
	v_cvt_pk_bf16_f32 v66, v64, v65
	v_cvt_pk_bf16_f32 v60, v174, v175
	v_cvt_pk_bf16_f32 v68, v68, v69
	v_cvt_pk_bf16_f32 v61, v176, v177
	v_cvt_pk_bf16_f32 v69, v70, v71
	v_cvt_pk_bf16_f32 v54, v178, v179
	v_cvt_pk_bf16_f32 v62, v72, v73
	v_cvt_pk_bf16_f32 v55, v180, v181
	v_cvt_pk_bf16_f32 v63, v74, v75
	v_cvt_pk_bf16_f32 v56, v182, v183
	v_cvt_pk_bf16_f32 v64, v80, v81
	v_cvt_pk_bf16_f32 v57, v184, v185
	v_cvt_pk_bf16_f32 v65, v82, v83
	s_branch .LBB0_446
